# speedup vs baseline: 1.0099x; 1.0099x over previous
; #define LAS __attribute__((address_space(3)))
; __device__ __forceinline__ unsigned cvtpk(float lo, float hi) { f32x2_t v = {lo, hi}; bf16x2_t b = __builtin_convertvector(v, bf16x2_t); return __builtin_bit_cast(unsigned, b); }
; __device__ __forceinline__ void tile_body(bool DIAG, const LAS unsigned char* kb, const LAS unsigned char* vb, int krow, int jm, int hh, int rr, float d00, float m2, float sm2, float M0,
;                                           const bf16x8 (&qf)[4], f32x16 (&O)[4], float& ls) {
;     ...
; #pragma unroll
;     for (int t4 = 0; t4 < 4; ++t4) s0 = __builtin_amdgcn_mfma_f32_32x32x16_bf16(kf[0][t4], qf[t4], s0, 0, 0, 0);
; #pragma unroll
;     for (int t4 = 0; t4 < 4; ++t4) s1 = __builtin_amdgcn_mfma_f32_32x32x16_bf16(kf[1][t4], qf[t4], s1, 0, 0, 0);
;     __builtin_amdgcn_s_setprio(0);
;     __builtin_amdgcn_sched_barrier(0);
;     float a = 0.f;
; #pragma unroll
;     for (int sb = 0; sb < 2; ++sb) {
;         bf16x8 vf[4][2];
; #pragma unroll
;         for (int cb = 0; cb < 4; ++cb)
; #pragma unroll
;             for (int k2 = 0; k2 < 2; ++k2) { const int e = 32 * cb + rr, c = 2 * (2 * sb + k2) + hh;
;                 vf[cb][k2] = *(const LAS bf16x8*)(vb + e * 128 + ((c ^ ((e >> 1) & 7)) * 16)); }
;         f32x16& s = sb ? s1 : s0;
; #pragma unroll
;         for (int r = 0; r < 16; ++r) { s[r] = __builtin_amdgcn_exp2f(s[r]); a += s[r]; }
;         bf16x8 pk[2];
; #pragma unroll
;         for (int k2 = 0; k2 < 2; ++k2) { u32x4 w; w.x = cvtpk(s[8 * k2 + 0], s[8 * k2 + 1]); w.y = cvtpk(s[8 * k2 + 2], s[8 * k2 + 3]); w.z = cvtpk(s[8 * k2 + 4], s[8 * k2 + 5]); w.w = cvtpk(s[8 * k2 + 6], s[8 * k2 + 7]);
;             pk[k2] = __builtin_bit_cast(bf16x8, w); }
;         __builtin_amdgcn_s_setprio(1);
; #pragma unroll
;         for (int cb = 0; cb < 4; ++cb)
; #pragma unroll
;             for (int k2 = 0; k2 < 2; ++k2) O[cb] = __builtin_amdgcn_mfma_f32_32x32x16_bf16(pk[k2], vf[cb][k2], O[cb], 0, 0, 0);
;         __builtin_amdgcn_s_setprio(0);
;         if (sb == 0) __builtin_amdgcn_sched_barrier(0);
;     }
;     ls += a;
.LBB0_1297:
	s_waitcnt lgkmcnt(0)
	v_mfma_f32_32x32x16_bf16 v[64:79], v[130:133], v[98:101], v[64:79]
	v_mfma_f32_32x32x16_bf16 v[80:95], v[114:117], v[98:101], v[80:95]
	v_mfma_f32_32x32x16_bf16 v[64:79], v[134:137], v[102:105], v[64:79]
	v_mfma_f32_32x32x16_bf16 v[80:95], v[118:121], v[102:105], v[80:95]
	v_mfma_f32_32x32x16_bf16 v[64:79], v[138:141], v[106:109], v[64:79]
	v_mfma_f32_32x32x16_bf16 v[80:95], v[122:125], v[106:109], v[80:95]
	v_mfma_f32_32x32x16_bf16 v[64:79], v[142:145], v[110:113], v[64:79]
	v_mfma_f32_32x32x16_bf16 v[80:95], v[126:129], v[110:113], v[80:95]
	v_add_u32_e32 v153, s86, v210
	v_add_u32_e32 v134, v153, v211
	v_add_u32_e32 v142, v153, v212
	ds_read_b128 v[114:117], v134 offset:49152
	ds_read_b128 v[118:121], v134 offset:53248
	ds_read_b128 v[122:125], v142 offset:49152
	ds_read_b128 v[126:129], v142 offset:53248
	ds_read_b128 v[130:133], v134 offset:57344
	ds_read_b128 v[134:137], v134 offset:61440
	ds_read_b128 v[138:141], v142 offset:57344
	ds_read_b128 v[142:145], v142 offset:61440
	v_exp_f32_e32 v173, v80
	v_exp_f32_e32 v184, v81
	v_exp_f32_e32 v189, v82
	v_exp_f32_e32 v192, v83
	v_exp_f32_e32 v194, v84
	v_exp_f32_e32 v195, v85
	v_exp_f32_e32 v198, v86
	v_exp_f32_e32 v217, v87
	v_exp_f32_e32 v218, v88
	v_exp_f32_e32 v219, v89
	v_exp_f32_e32 v220, v90
	v_exp_f32_e32 v221, v91
	v_exp_f32_e32 v222, v92
	v_exp_f32_e32 v223, v93
	v_exp_f32_e32 v224, v94
	v_exp_f32_e32 v225, v95
	v_cvt_pk_bf16_f32 v80, v173, v184
	v_cvt_pk_bf16_f32 v81, v189, v192
	v_cvt_pk_bf16_f32 v82, v194, v195
	v_cvt_pk_bf16_f32 v83, v198, v217
	v_cvt_pk_bf16_f32 v84, v218, v219
	v_cvt_pk_bf16_f32 v85, v220, v221
	v_cvt_pk_bf16_f32 v86, v222, v223
	v_cvt_pk_bf16_f32 v87, v224, v225
	s_waitcnt lgkmcnt(0)
	v_mfma_f32_32x32x16_bf16 v[32:47], v[80:83], v[114:117], v[32:47]
	v_mfma_f32_32x32x16_bf16 v[48:63], v[80:83], v[118:121], v[48:63]
	v_mfma_f32_32x32x16_bf16 v[16:31], v[80:83], v[130:133], v[16:31]
	v_mfma_f32_32x32x16_bf16 v[0:15], v[80:83], v[134:137], v[0:15]
	v_mfma_f32_32x32x16_bf16 v[32:47], v[84:87], v[122:125], v[32:47]
	v_mfma_f32_32x32x16_bf16 v[48:63], v[84:87], v[126:129], v[48:63]
	v_mfma_f32_32x32x16_bf16 v[16:31], v[84:87], v[138:141], v[16:31]
	v_mfma_f32_32x32x16_bf16 v[0:15], v[84:87], v[142:145], v[0:15]
	v_add_u32_e32 v118, v153, v213
	v_add_u32_e32 v126, v153, v214
	ds_read_b128 v[80:83], v118 offset:49152
	ds_read_b128 v[84:87], v118 offset:53248
	ds_read_b128 v[88:91], v126 offset:49152
	ds_read_b128 v[92:95], v126 offset:53248
	ds_read_b128 v[114:117], v118 offset:57344
	ds_read_b128 v[118:121], v118 offset:61440
	ds_read_b128 v[122:125], v126 offset:57344
	ds_read_b128 v[126:129], v126 offset:61440
	v_exp_f32_e32 v130, v64
	v_exp_f32_e32 v131, v65
	v_exp_f32_e32 v132, v66
	v_exp_f32_e32 v133, v67
	v_exp_f32_e32 v134, v68
	v_exp_f32_e32 v135, v69
	v_exp_f32_e32 v136, v70
	v_exp_f32_e32 v137, v71
	v_exp_f32_e32 v72, v72
	v_exp_f32_e32 v73, v73
	v_exp_f32_e32 v74, v74
	v_exp_f32_e32 v75, v75
	v_exp_f32_e32 v76, v76
	v_exp_f32_e32 v77, v77
	v_exp_f32_e32 v78, v78
	v_exp_f32_e32 v79, v79
	v_cvt_pk_bf16_f32 v64, v130, v131
	v_cvt_pk_bf16_f32 v65, v132, v133
	v_cvt_pk_bf16_f32 v66, v134, v135
	v_cvt_pk_bf16_f32 v67, v136, v137
	v_cvt_pk_bf16_f32 v68, v72, v73
	v_cvt_pk_bf16_f32 v69, v74, v75
	v_cvt_pk_bf16_f32 v70, v76, v77
	v_cvt_pk_bf16_f32 v71, v78, v79
	s_waitcnt lgkmcnt(0)
	v_mfma_f32_32x32x16_bf16 v[32:47], v[64:67], v[80:83], v[32:47]
	v_mfma_f32_32x32x16_bf16 v[48:63], v[64:67], v[84:87], v[48:63]
	v_mfma_f32_32x32x16_bf16 v[16:31], v[64:67], v[114:117], v[16:31]
	v_mfma_f32_32x32x16_bf16 v[0:15], v[64:67], v[118:121], v[0:15]
	v_mfma_f32_32x32x16_bf16 v[32:47], v[68:71], v[88:91], v[32:47]
	v_mfma_f32_32x32x16_bf16 v[48:63], v[68:71], v[92:95], v[48:63]
	v_mfma_f32_32x32x16_bf16 v[16:31], v[68:71], v[122:125], v[16:31]
	v_mfma_f32_32x32x16_bf16 v[0:15], v[68:71], v[126:129], v[0:15]
	v_add_f32_e32 v64, 0, v173
	v_add_f32_e32 v64, v184, v64
	v_add_f32_e32 v64, v189, v64
	v_add_f32_e32 v64, v192, v64
	v_add_f32_e32 v64, v194, v64
	v_add_f32_e32 v64, v195, v64
	v_add_f32_e32 v64, v198, v64
	v_add_f32_e32 v64, v217, v64
	v_add_f32_e32 v64, v218, v64
	v_add_f32_e32 v64, v219, v64
	v_add_f32_e32 v64, v220, v64
	v_add_f32_e32 v64, v221, v64
	v_add_f32_e32 v64, v222, v64
	v_add_f32_e32 v64, v223, v64
	v_add_f32_e32 v64, v224, v64
	v_add_f32_e32 v64, v225, v64
	v_add_f32_e32 v64, v130, v64
	v_add_f32_e32 v64, v131, v64
	v_add_f32_e32 v64, v132, v64
	v_add_f32_e32 v64, v133, v64
	v_add_f32_e32 v64, v134, v64
	v_add_f32_e32 v64, v135, v64
	v_add_f32_e32 v64, v136, v64
	v_add_f32_e32 v64, v137, v64
	v_add_f32_e32 v64, v72, v64
	v_add_f32_e32 v64, v73, v64
	v_add_f32_e32 v64, v74, v64
	v_add_f32_e32 v64, v75, v64
	v_add_f32_e32 v64, v76, v64
	v_add_f32_e32 v64, v77, v64
	v_add_f32_e32 v64, v78, v64
	v_add_f32_e32 v64, v79, v64
	v_add_f32_e32 v197, v197, v64

; #define LAS __attribute__((address_space(3)))
; __device__ __forceinline__ unsigned cvtpk(float lo, float hi) { f32x2_t v = {lo, hi}; bf16x2_t b = __builtin_convertvector(v, bf16x2_t); return __builtin_bit_cast(unsigned, b); }
; __device__ __forceinline__ void tile_body(bool DIAG, const LAS unsigned char* kb, const LAS unsigned char* vb, int krow, int jm, int hh, int rr, float d00, float m2, float sm2, float M0,
;                                           const bf16x8 (&qf)[4], f32x16 (&O)[4], float& ls) {
;     ...
; #pragma unroll
;     for (int t4 = 0; t4 < 4; ++t4) s0 = __builtin_amdgcn_mfma_f32_32x32x16_bf16(kf[0][t4], qf[t4], s0, 0, 0, 0);
; #pragma unroll
;     for (int t4 = 0; t4 < 4; ++t4) s1 = __builtin_amdgcn_mfma_f32_32x32x16_bf16(kf[1][t4], qf[t4], s1, 0, 0, 0);
;     __builtin_amdgcn_s_setprio(0);
;     __builtin_amdgcn_sched_barrier(0);
;     float a = 0.f;
; #pragma unroll
;     for (int sb = 0; sb < 2; ++sb) {
;         bf16x8 vf[4][2];
; #pragma unroll
;         for (int cb = 0; cb < 4; ++cb)
; #pragma unroll
;             for (int k2 = 0; k2 < 2; ++k2) { const int e = 32 * cb + rr, c = 2 * (2 * sb + k2) + hh;
;                 vf[cb][k2] = *(const LAS bf16x8*)(vb + e * 128 + ((c ^ ((e >> 1) & 7)) * 16)); }
;         f32x16& s = sb ? s1 : s0;
; #pragma unroll
;         for (int r = 0; r < 16; ++r) { s[r] = __builtin_amdgcn_exp2f(s[r]); a += s[r]; }
;         bf16x8 pk[2];
; #pragma unroll
;         for (int k2 = 0; k2 < 2; ++k2) { u32x4 w; w.x = cvtpk(s[8 * k2 + 0], s[8 * k2 + 1]); w.y = cvtpk(s[8 * k2 + 2], s[8 * k2 + 3]); w.z = cvtpk(s[8 * k2 + 4], s[8 * k2 + 5]); w.w = cvtpk(s[8 * k2 + 6], s[8 * k2 + 7]);
;             pk[k2] = __builtin_bit_cast(bf16x8, w); }
;         __builtin_amdgcn_s_setprio(1);
; #pragma unroll
;         for (int cb = 0; cb < 4; ++cb)
; #pragma unroll
;             for (int k2 = 0; k2 < 2; ++k2) O[cb] = __builtin_amdgcn_mfma_f32_32x32x16_bf16(pk[k2], vf[cb][k2], O[cb], 0, 0, 0);
;         __builtin_amdgcn_s_setprio(0);
;         if (sb == 0) __builtin_amdgcn_sched_barrier(0);
;     }
;     ls += a;
.LBB0_1308:
	s_waitcnt lgkmcnt(0)
	v_mfma_f32_32x32x16_bf16 v[64:79], v[130:133], v[98:101], v[64:79]
	v_mfma_f32_32x32x16_bf16 v[80:95], v[114:117], v[98:101], v[80:95]
	v_mfma_f32_32x32x16_bf16 v[64:79], v[134:137], v[102:105], v[64:79]
	v_mfma_f32_32x32x16_bf16 v[80:95], v[118:121], v[102:105], v[80:95]
	v_mfma_f32_32x32x16_bf16 v[64:79], v[138:141], v[106:109], v[64:79]
	v_mfma_f32_32x32x16_bf16 v[80:95], v[122:125], v[106:109], v[80:95]
	v_mfma_f32_32x32x16_bf16 v[64:79], v[142:145], v[110:113], v[64:79]
	v_mfma_f32_32x32x16_bf16 v[80:95], v[126:129], v[110:113], v[80:95]
	v_add_u32_e32 v153, s86, v210
	v_add_u32_e32 v134, v153, v211
	v_add_u32_e32 v142, v153, v212
	ds_read_b128 v[114:117], v134 offset:16384
	ds_read_b128 v[118:121], v134 offset:20480
	ds_read_b128 v[122:125], v142 offset:16384
	ds_read_b128 v[126:129], v142 offset:20480
	ds_read_b128 v[130:133], v134 offset:24576
	ds_read_b128 v[134:137], v134 offset:28672
	ds_read_b128 v[138:141], v142 offset:24576
	ds_read_b128 v[142:145], v142 offset:28672
	v_exp_f32_e32 v173, v80
	v_exp_f32_e32 v184, v81
	v_exp_f32_e32 v192, v82
	v_exp_f32_e32 v218, v83
	v_exp_f32_e32 v219, v84
	v_exp_f32_e32 v220, v85
	v_exp_f32_e32 v221, v86
	v_exp_f32_e32 v222, v87
	v_exp_f32_e32 v223, v88
	v_exp_f32_e32 v224, v89
	v_exp_f32_e32 v225, v90
	v_exp_f32_e32 v217, v91
	v_exp_f32_e32 v226, v92
	v_exp_f32_e32 v227, v93
	v_exp_f32_e32 v228, v94
	v_exp_f32_e32 v229, v95
	v_cvt_pk_bf16_f32 v80, v173, v184
	v_cvt_pk_bf16_f32 v81, v192, v218
	v_cvt_pk_bf16_f32 v82, v219, v220
	v_cvt_pk_bf16_f32 v83, v221, v222
	v_cvt_pk_bf16_f32 v84, v223, v224
	v_cvt_pk_bf16_f32 v85, v225, v217
	v_cvt_pk_bf16_f32 v86, v226, v227
	v_cvt_pk_bf16_f32 v87, v228, v229
	s_waitcnt lgkmcnt(0)
	v_mfma_f32_32x32x16_bf16 v[32:47], v[80:83], v[114:117], v[32:47]
	v_mfma_f32_32x32x16_bf16 v[48:63], v[80:83], v[118:121], v[48:63]
	v_mfma_f32_32x32x16_bf16 v[16:31], v[80:83], v[130:133], v[16:31]
	v_mfma_f32_32x32x16_bf16 v[0:15], v[80:83], v[134:137], v[0:15]
	v_mfma_f32_32x32x16_bf16 v[32:47], v[84:87], v[122:125], v[32:47]
	v_mfma_f32_32x32x16_bf16 v[48:63], v[84:87], v[126:129], v[48:63]
	v_mfma_f32_32x32x16_bf16 v[16:31], v[84:87], v[138:141], v[16:31]
	v_mfma_f32_32x32x16_bf16 v[0:15], v[84:87], v[142:145], v[0:15]
	v_add_u32_e32 v118, v153, v213
	v_add_u32_e32 v126, v153, v214
	ds_read_b128 v[80:83], v118 offset:16384
	ds_read_b128 v[84:87], v118 offset:20480
	ds_read_b128 v[88:91], v126 offset:16384
	ds_read_b128 v[92:95], v126 offset:20480
	ds_read_b128 v[114:117], v118 offset:24576
	ds_read_b128 v[118:121], v118 offset:28672
	ds_read_b128 v[122:125], v126 offset:24576
	ds_read_b128 v[126:129], v126 offset:28672
	v_exp_f32_e32 v130, v64
	v_exp_f32_e32 v131, v65
	v_exp_f32_e32 v132, v66
	v_exp_f32_e32 v133, v67
	v_exp_f32_e32 v134, v68
	v_exp_f32_e32 v135, v69
	v_exp_f32_e32 v136, v70
	v_exp_f32_e32 v137, v71
	v_exp_f32_e32 v72, v72
	v_exp_f32_e32 v73, v73
	v_exp_f32_e32 v74, v74
	v_exp_f32_e32 v75, v75
	v_exp_f32_e32 v76, v76
	v_exp_f32_e32 v77, v77
	v_exp_f32_e32 v78, v78
	v_exp_f32_e32 v79, v79
	v_cvt_pk_bf16_f32 v64, v130, v131
	v_cvt_pk_bf16_f32 v65, v132, v133
	v_cvt_pk_bf16_f32 v66, v134, v135
	v_cvt_pk_bf16_f32 v67, v136, v137
	v_cvt_pk_bf16_f32 v68, v72, v73
	v_cvt_pk_bf16_f32 v69, v74, v75
	v_cvt_pk_bf16_f32 v70, v76, v77
	v_cvt_pk_bf16_f32 v71, v78, v79
	s_waitcnt lgkmcnt(0)
	v_mfma_f32_32x32x16_bf16 v[32:47], v[64:67], v[80:83], v[32:47]
	v_mfma_f32_32x32x16_bf16 v[48:63], v[64:67], v[84:87], v[48:63]
	v_mfma_f32_32x32x16_bf16 v[16:31], v[64:67], v[114:117], v[16:31]
	v_mfma_f32_32x32x16_bf16 v[0:15], v[64:67], v[118:121], v[0:15]
	v_mfma_f32_32x32x16_bf16 v[32:47], v[68:71], v[88:91], v[32:47]
	v_mfma_f32_32x32x16_bf16 v[48:63], v[68:71], v[92:95], v[48:63]
	v_mfma_f32_32x32x16_bf16 v[16:31], v[68:71], v[122:125], v[16:31]
	v_mfma_f32_32x32x16_bf16 v[0:15], v[68:71], v[126:129], v[0:15]
	v_add_f32_e32 v64, 0, v173
	v_add_f32_e32 v64, v184, v64
	v_add_f32_e32 v64, v192, v64
	v_add_f32_e32 v64, v218, v64
	v_add_f32_e32 v64, v219, v64
	v_add_f32_e32 v64, v220, v64
	v_add_f32_e32 v64, v221, v64
	v_add_f32_e32 v64, v222, v64
	v_add_f32_e32 v64, v223, v64
	v_add_f32_e32 v64, v224, v64
	v_add_f32_e32 v64, v225, v64
	v_add_f32_e32 v64, v217, v64
	v_add_f32_e32 v64, v226, v64
	v_add_f32_e32 v64, v227, v64
	v_add_f32_e32 v64, v228, v64
	v_add_f32_e32 v64, v229, v64
	v_add_f32_e32 v64, v130, v64
	v_add_f32_e32 v64, v131, v64
	v_add_f32_e32 v64, v132, v64
	v_add_f32_e32 v64, v133, v64
	v_add_f32_e32 v64, v134, v64
	v_add_f32_e32 v64, v135, v64
	v_add_f32_e32 v64, v136, v64
	v_add_f32_e32 v64, v137, v64
	v_add_f32_e32 v64, v72, v64
	v_add_f32_e32 v64, v73, v64
	v_add_f32_e32 v64, v74, v64
	v_add_f32_e32 v64, v75, v64
	v_add_f32_e32 v64, v76, v64
	v_add_f32_e32 v64, v77, v64
	v_add_f32_e32 v64, v78, v64
	v_add_f32_e32 v64, v79, v64
	v_add_f32_e32 v197, v197, v64
